# SSD prompt: hoist csf reads (3b) and x/z u16 reads (4a) out of per-value LDS round-trip chains
# speedup vs baseline: 1.0027x; 1.0027x over previous
.LBB0_854:
	s_or_b64 exec, exec, s[78:79]
	ds_read_b32 v47, v134
	ds_read_b32 v46, v135
	ds_read_b32 v210, v126
	ds_read_b32 v211, v128
	ds_read_b32 v212, v130
	ds_read_b32 v213, v132
	s_and_saveexec_b64 s[78:79], s[24:25]
	s_cbranch_execz .LBB0_856
	s_waitcnt lgkmcnt(0)
	v_sub_f32_e32 v48, v210, v47
	v_mul_f32_e32 v48, 0x3fb8aa3b, v48
	v_exp_f32_e32 v48, v48
	s_nop 0
	v_mul_f32_e32 v42, v42, v48
	v_mul_f32_e32 v48, v46, v42
.LBB0_856:
	s_or_b64 exec, exec, s[78:79]
	s_nop 1
	v_bfe_u32 v42, v48, 16, 1
	v_add3_u32 v42, v48, v42, s88
	v_add_u32_e32 v48, v136, v127
	ds_write_b16_d16_hi v48, v42
	v_mov_b32_e32 v42, 0
	v_mov_b32_e32 v48, 0
	s_and_saveexec_b64 s[78:79], s[26:27]
	s_cbranch_execz .LBB0_858
	s_waitcnt lgkmcnt(0)
	v_sub_f32_e32 v48, v211, v47
	v_mul_f32_e32 v48, 0x3fb8aa3b, v48
	v_exp_f32_e32 v48, v48
	s_nop 0
	v_mul_f32_e32 v43, v43, v48
	v_mul_f32_e32 v48, v46, v43
.LBB0_858:
	s_or_b64 exec, exec, s[78:79]
	v_bfe_u32 v43, v48, 16, 1
	v_add3_u32 v43, v48, v43, s88
	v_add_u32_e32 v48, v136, v129
	ds_write_b16_d16_hi v48, v43
	s_and_saveexec_b64 s[78:79], s[28:29]
	s_cbranch_execz .LBB0_860
	s_waitcnt lgkmcnt(0)
	v_sub_f32_e32 v42, v212, v47
	v_mul_f32_e32 v42, 0x3fb8aa3b, v42
	v_exp_f32_e32 v42, v42
	s_nop 0
	v_mul_f32_e32 v42, v44, v42
	v_mul_f32_e32 v42, v46, v42
.LBB0_860:
	s_or_b64 exec, exec, s[78:79]
	v_bfe_u32 v43, v42, 16, 1
	v_add3_u32 v42, v42, v43, s88
	v_add_u32_e32 v43, v136, v131
	ds_write_b16_d16_hi v43, v42
	v_mov_b32_e32 v42, 0
	v_mov_b32_e32 v43, 0
	s_and_saveexec_b64 s[78:79], s[30:31]
	s_cbranch_execz .LBB0_862
	s_waitcnt lgkmcnt(0)
	v_sub_f32_e32 v43, v213, v47
	v_mul_f32_e32 v43, 0x3fb8aa3b, v43
	v_exp_f32_e32 v43, v43
	s_nop 0
	v_mul_f32_e32 v43, v45, v43
	v_mul_f32_e32 v43, v46, v43

.LBB0_864:
	s_or_b64 exec, exec, s[78:79]
	s_waitcnt lgkmcnt(5)
	ds_read_b32 v47, v137
	s_waitcnt lgkmcnt(5)
	ds_read_b32 v46, v138
	v_mov_b32_e32 v48, 0
	v_mov_b32_e32 v49, 0
	s_and_saveexec_b64 s[78:79], s[34:35]
	s_cbranch_execz .LBB0_866
	s_waitcnt lgkmcnt(0)
	v_sub_f32_e32 v49, v210, v47
	v_mul_f32_e32 v49, 0x3fb8aa3b, v49
	v_exp_f32_e32 v49, v49
	s_nop 0
	v_mul_f32_e32 v42, v42, v49
	v_mul_f32_e32 v49, v46, v42
.LBB0_866:
	s_or_b64 exec, exec, s[78:79]
	v_bfe_u32 v42, v49, 16, 1
	v_add3_u32 v42, v49, v42, s88
	ds_write_b16_d16_hi v139, v42
	s_and_saveexec_b64 s[78:79], s[36:37]
	s_cbranch_execz .LBB0_868
	s_waitcnt lgkmcnt(0)
	v_sub_f32_e32 v42, v211, v47
	v_mul_f32_e32 v42, 0x3fb8aa3b, v42
	v_exp_f32_e32 v42, v42
	s_nop 0
	v_mul_f32_e32 v42, v43, v42
	v_mul_f32_e32 v48, v46, v42
.LBB0_868:
	s_or_b64 exec, exec, s[78:79]
	v_bfe_u32 v42, v48, 16, 1
	v_add3_u32 v42, v48, v42, s88
	ds_write_b16_d16_hi v140, v42
	v_mov_b32_e32 v42, 0
	v_mov_b32_e32 v43, 0
	s_and_saveexec_b64 s[78:79], s[38:39]
	s_cbranch_execz .LBB0_870
	s_waitcnt lgkmcnt(0)
	v_sub_f32_e32 v43, v212, v47
	v_mul_f32_e32 v43, 0x3fb8aa3b, v43
	v_exp_f32_e32 v43, v43
	s_nop 0
	v_mul_f32_e32 v43, v44, v43
	v_mul_f32_e32 v43, v46, v43
.LBB0_870:
	s_or_b64 exec, exec, s[78:79]
	v_bfe_u32 v44, v43, 16, 1
	v_add3_u32 v43, v43, v44, s88
	ds_write_b16_d16_hi v141, v43
	s_and_saveexec_b64 s[78:79], s[40:41]
	s_cbranch_execz .LBB0_872
	s_waitcnt lgkmcnt(0)
	v_sub_f32_e32 v42, v213, v47
	v_mul_f32_e32 v42, 0x3fb8aa3b, v42
	v_exp_f32_e32 v42, v42
	s_nop 0
	v_mul_f32_e32 v42, v45, v42
	v_mul_f32_e32 v42, v46, v42

.LBB0_875:
	ds_read_u16 v214, v144 offset:2
	ds_read_u16 v215, v147
	ds_read_u16 v216, v144 offset:4
	ds_read_u16 v217, v149
	ds_read_u16 v218, v144 offset:6
	ds_read_u16 v219, v151
	ds_read_u16 v188, v144
	ds_read_u16 v189, v145
	ds_read_b128 v[192:195], v126
	s_andn2_b64 vcc, exec, s[78:79]
	s_waitcnt lgkmcnt(2)
	v_lshlrev_b32_e32 v188, 16, v188
	s_waitcnt lgkmcnt(0)
	v_mul_f32_e32 v190, 0x3fb8aa3b, v192
	v_exp_f32_e32 v192, v190
	v_lshlrev_b32_e32 v190, 16, v189
	v_mul_f32_e32 v189, 0x3fb8aa3b, v193
	v_exp_f32_e32 v189, v189
	v_fma_f32 v50, v54, v192, v50
	v_fmac_f32_e32 v50, v183, v188
	v_mul_f32_e32 v188, v50, v190
	v_bfe_u32 v50, v188, 16, 1
	v_add3_u32 v50, v188, v50, s88
	ds_write_b16_d16_hi v146, v50
	v_fma_f32 v51, v55, v189, v51
	v_mul_f32_e32 v190, 0x3fb8aa3b, v194
	v_exp_f32_e32 v190, v190
	v_lshlrev_b32_e32 v50, 16, v214
	v_lshlrev_b32_e32 v54, 16, v215
	v_fmac_f32_e32 v51, v183, v50
	v_mul_f32_e32 v54, v51, v54
	v_bfe_u32 v50, v54, 16, 1
	v_add3_u32 v50, v54, v50, s88
	ds_write_b16_d16_hi v148, v50
	v_fma_f32 v52, v56, v190, v52
	v_mul_f32_e32 v55, 0x3fb8aa3b, v195
	v_lshlrev_b32_e32 v50, 16, v216
	v_lshlrev_b32_e32 v51, 16, v217
	v_fmac_f32_e32 v52, v183, v50
	v_mul_f32_e32 v51, v52, v51
	v_bfe_u32 v50, v51, 16, 1
	v_add3_u32 v50, v51, v50, s88
	ds_write_b16_d16_hi v150, v50
	v_exp_f32_e32 v52, v55
	s_nop 0
	v_fmac_f32_e32 v53, v57, v52
	v_lshlrev_b32_e32 v50, 16, v218
	v_lshlrev_b32_e32 v55, 16, v219
	v_fmac_f32_e32 v53, v183, v50
	v_mul_f32_e32 v50, v53, v55
	v_bfe_u32 v53, v50, 16, 1
	v_add3_u32 v53, v50, v53, s88
	ds_write_b16_d16_hi v152, v53
	v_add_u32_e32 v53, v110, v153
	ds_read_b128 v[194:197], v53
	ds_read_b128 v[198:201], v53 offset:64
	s_waitcnt lgkmcnt(1)
	v_mfma_f32_16x16x32_bf16 v[46:49], v[46:49], v[194:197], 0
	s_waitcnt lgkmcnt(0)
	v_mfma_f32_16x16x32_bf16 v[42:45], v[42:45], v[198:201], v[46:49]
	s_cbranch_vccnz .LBB0_877
	s_nop 4
	ds_read_b128 v[46:49], v108
	ds_read_b128 v[194:197], v108 offset:64
	ds_read_b128 v[198:201], v182 offset:39168
	ds_read_b128 v[202:205], v182 offset:39232
	s_waitcnt lgkmcnt(1)
	v_mfma_f32_16x16x32_bf16 v[46:49], v[46:49], v[198:201], 0
	ds_read_b128 v[198:201], v108 offset:128
	ds_read_b128 v[206:209], v108 offset:192
	s_waitcnt lgkmcnt(2)
	v_mfma_f32_16x16x32_bf16 v[46:49], v[194:197], v[202:205], v[46:49]
	ds_read_b128 v[194:197], v182 offset:39296
	ds_read_b128 v[202:205], v182 offset:39360
	s_waitcnt lgkmcnt(1)
	v_mfma_f32_16x16x32_bf16 v[46:49], v[198:201], v[194:197], v[46:49]
	s_waitcnt lgkmcnt(0)
	v_mfma_f32_16x16x32_bf16 v[46:49], v[206:209], v[202:205], v[46:49]
	s_branch .LBB0_878

.LBB0_878:
	ds_read_u16 v220, v154 offset:2
	ds_read_u16 v221, v157
	ds_read_u16 v222, v154 offset:4
	ds_read_u16 v223, v159
	ds_read_u16 v224, v154 offset:6
	ds_read_u16 v225, v161
	ds_read_u16 v53, v154
	ds_read_u16 v55, v155
	s_nop 4
	v_fma_f32 v42, v192, v46, v42
	v_fma_f32 v43, v189, v47, v43
	v_fma_f32 v44, v190, v48, v44
	s_waitcnt lgkmcnt(1)
	v_lshlrev_b32_e32 v46, 16, v53
	s_waitcnt lgkmcnt(0)
	v_lshlrev_b32_e32 v53, 16, v55
	v_fmac_f32_e32 v42, v183, v46
	v_mul_f32_e32 v53, v42, v53
	v_bfe_u32 v42, v53, 16, 1
	v_add3_u32 v42, v53, v42, s88
	ds_write_b16_d16_hi v156, v42
	v_fmac_f32_e32 v45, v52, v49
	v_mul_f32_e32 v48, v53, v53
	v_fmac_f32_e32 v48, v188, v188
	v_lshlrev_b32_e32 v42, 16, v220
	v_lshlrev_b32_e32 v46, 16, v221
	v_fmac_f32_e32 v43, v183, v42
	v_mul_f32_e32 v46, v43, v46
	v_bfe_u32 v42, v46, 16, 1
	v_add3_u32 v42, v46, v42, s88
	ds_write_b16_d16_hi v158, v42
	v_add_f32_dpp v48, v48, v48 quad_perm:[1,0,3,2] row_mask:0xf bank_mask:0xf bound_ctrl:1
	v_add_u32_e32 v42, s77, v185
	v_lshlrev_b32_e32 v43, 16, v222
	v_lshlrev_b32_e32 v47, 16, v223
	v_fmac_f32_e32 v44, v183, v43
	v_mul_f32_e32 v47, v44, v47
	v_bfe_u32 v43, v47, 16, 1
	v_add3_u32 v43, v47, v43, s88
	ds_write_b16_d16_hi v160, v43
	v_lshlrev_b32_e32 v43, 16, v224
	v_lshlrev_b32_e32 v44, 16, v225
	v_fmac_f32_e32 v45, v183, v43
	v_mul_f32_e32 v44, v45, v44
	v_bfe_u32 v43, v44, 16, 1
	v_add3_u32 v43, v44, v43, s88
	ds_write_b16_d16_hi v162, v43
	s_nop 0
	v_add_f32_dpp v43, v48, v48 quad_perm:[2,3,0,1] row_mask:0xf bank_mask:0xf bound_ctrl:1
	s_nop 1
	v_add_f32_dpp v45, v43, v43 row_half_mirror row_mask:0xf bank_mask:0xf bound_ctrl:1
	s_nop 1
	v_mov_b32_dpp v48, v45 row_mirror row_mask:0xf bank_mask:0xf bound_ctrl:1
	s_and_saveexec_b64 s[78:79], s[6:7]
	s_cbranch_execz .LBB0_880
	v_ashrrev_i32_e32 v43, 31, v42
	v_lshl_add_u64 v[52:53], v[42:43], 4, s[42:43]
	v_add_f32_e32 v43, v45, v48
	global_atomic_add_f32 v[52:53], v43, off
